# diff attention: row-sum MFMA results folded into lrun off the critical path (no s_nop stall), temporaries renamed out of the MFMA destination range
# baseline (speedup 1.0000x reference)
; #define AT_LSTOREK(buf) do { LAS unsigned char* d_ = lds + (buf) * AT_BUF; \
;         *(LAS u32x4*)(d_ + wave * 1024 + lane * 16) = kreg; \
;         if (MODE == 0 && wave < 4) *(LAS u32x4*)(d_ + (8 + wave) * 1024 + lane * 16) = kreg2; } while (0)
; #define AT_LSTOREV(buf) do { LAS unsigned char* d_ = lds + (buf) * AT_BUF; \
;         *(LAS u32x4*)(d_ + AT_V + wave * 1024 + lane * 16) = vreg; } while (0)
; template <int MODE, int NQ>
; __device__ __forceinline__ void attn_unit(LAS unsigned char* lds, const Params& P, int layer, int b, int h, int qb) {
;     ...
;                     f32x16 t = __builtin_amdgcn_mfma_f32_32x32x16_bf16(ones8, pw[cc][0], f32x16{}, 0, 0, 0);
;                     t = __builtin_amdgcn_mfma_f32_32x32x16_bf16(ones8, pw[cc][1], t, 0, 0, 0);
;                     lrun[cc] += t[0];
;     ...
;             if (it + 2 < NT) { if (hf == 0) AT_LSTOREK(bn2); else AT_LSTOREV(bn2); }
;         }
;         __syncthreads();
;         bcur = bnx;
.LBB0_409:
	s_addk_i32 s8, 0x100
	s_add_i32 s7, s7, 1
	s_cmpk_eq_i32 s8, 0x1e00
	s_waitcnt vmcnt(0)
	v_add_f32_e32 v187, v187, v80
	ds_write_b128 v202, v[2:5]
	ds_write_b128 v202, v[224:227] offset:12288
	s_waitcnt lgkmcnt(0)
	s_barrier
	s_cbranch_scc1 .LBB0_434

; template <int MODE, int NQ>
; __device__ __forceinline__ void attn_unit(LAS unsigned char* lds, const Params& P, int layer, int b, int h, int qb) {
;     ...
;                     const LAS f32x4* tp4 = (const LAS f32x4*)(tlane + (kt * 64 + hf * 32) * 4);
;                     float rm = -3e38f;
; #pragma unroll
;                     for (int g = 0; g < 4; ++g) { const f32x4 t4 = tp4[2 * g];
; #pragma unroll
;                         for (int i = 0; i < 4; ++i) { s0[4 * g + i] = s0[4 * g + i] * c + t4[i]; rm = fmaxf(rm, s0[4 * g + i]); } }
;                     rm = xmax(rm);
;                     mn = fmaxf(mrun[cc], rm);
;                     rmrel[cc] = rm;
;                 } else {
;                     float rm = -3e38f;
; #pragma unroll
;                     for (int r = 0; r < 16; ++r) rm = fmaxf(rm, s0[r]);
;                     rm = xmax(rm);
;                     mn = fmaxf(mrun[cc], rm * c);
;                 }
;                 if (__any(mn > mrun[cc] + AT_THR)) {
;                     const float al = fast_exp2(mrun[cc] - mn); lrun[cc] *= al;
; #pragma unroll
;                     for (int r = 0; r < 16; ++r) { o[cc][0][r] *= al; o[cc][1][r] *= al; }
;                     mrun[cc] = mn;
;                 }
;                 mn = mrun[cc];
;                 if (MODE != 0) rmrel[cc] -= mn;
;                 const bool dead = (MODE != 0) && __all(rmrel[cc] < -136.f);
;                 if (dead) { pw[cc][0] = zero8; pw[cc][1] = zero8; }
;                 else {
;                     alive = true;
;                     if (MODE != 0) {
; #pragma unroll
;                         for (int r = 0; r < 16; ++r) s0[r] = fast_exp2(s0[r] - mn);
;                     } else {
;                         const float nm = -mn;
; #pragma unroll
;                         for (int r = 0; r < 16; ++r) s0[r] = fast_exp2(__builtin_fmaf(s0[r], c, nm));
;                     }
;                     u32x4 w;
;                     w.x = cvtpk(s0[0], s0[1]); w.y = cvtpk(s0[2], s0[3]); w.z = cvtpk(s0[4], s0[5]); w.w = cvtpk(s0[6], s0[7]); pw[cc][0] = __builtin_bit_cast(bf16x8, w);
;                     w.x = cvtpk(s0[8], s0[9]); w.y = cvtpk(s0[10], s0[11]); w.z = cvtpk(s0[12], s0[13]); w.w = cvtpk(s0[14], s0[15]); pw[cc][1] = __builtin_bit_cast(bf16x8, w);
;                     f32x16 t = __builtin_amdgcn_mfma_f32_32x32x16_bf16(ones8, pw[cc][0], f32x16{}, 0, 0, 0);
.Lr0_A1_join:
	v_cvt_pk_bf16_f32 v168, v108, v109
	v_cvt_pk_bf16_f32 v169, v98, v99
	v_cvt_pk_bf16_f32 v170, v14, v15
	v_cvt_pk_bf16_f32 v171, v96, v97
	v_cvt_pk_bf16_f32 v160, v104, v105
	v_cvt_pk_bf16_f32 v161, v100, v101
	v_cvt_pk_bf16_f32 v162, v102, v103
	v_cvt_pk_bf16_f32 v163, v106, v107
	v_mfma_f32_32x32x16_bf16 v[96:111], v[220:223], v[168:171], 0
	s_nop 0
	v_mfma_f32_32x32x16_bf16 v[96:111], v[220:223], v[160:163], v[96:111]
	s_branch .LBB0_416
.LBB0_415:
	v_mov_b32_e32 v96, 0
	v_mov_b32_e32 v160, 0
	v_mov_b32_e32 v161, v160
	v_mov_b32_e32 v162, v160
	v_mov_b32_e32 v163, v160
	v_mov_b32_e32 v168, v160
	v_mov_b32_e32 v169, v160
	v_mov_b32_e32 v170, v160
	v_mov_b32_e32 v171, v160
.LBB0_416:
	v_fmamk_f32 v204, v80, 0x3e8293ee, v156
	v_fmamk_f32 v205, v81, 0x3e8293ee, v157
	v_max3_f32 v14, v204, s68, v205
	v_fmamk_f32 v206, v82, 0x3e8293ee, v158
	v_fmac_f32_e32 v159, 0x3e8293ee, v83
	v_max3_f32 v14, v14, v206, v159
	v_fmamk_f32 v207, v84, 0x3e8293ee, v152
	v_fmamk_f32 v83, v85, 0x3e8293ee, v153
	v_max3_f32 v14, v14, v207, v83
	v_fmamk_f32 v84, v86, 0x3e8293ee, v154
	v_fmac_f32_e32 v155, 0x3e8293ee, v87
	v_max3_f32 v14, v14, v84, v155
	v_add_f32_e32 v188, v188, v96
	v_fmamk_f32 v85, v88, 0x3e8293ee, v164
	v_fmamk_f32 v80, v89, 0x3e8293ee, v165
	v_max3_f32 v14, v14, v85, v80
	v_fmamk_f32 v81, v90, 0x3e8293ee, v166
	v_fmac_f32_e32 v167, 0x3e8293ee, v91
	v_max3_f32 v15, v14, v81, v167
	v_fmamk_f32 v82, v92, 0x3e8293ee, v172
	v_fmamk_f32 v14, v93, 0x3e8293ee, v173
	v_max3_f32 v86, v15, v82, v14
	v_fmamk_f32 v15, v94, 0x3e8293ee, v174
	v_fmac_f32_e32 v175, 0x3e8293ee, v95
	v_max3_f32 v86, v86, v15, v175
	v_mov_b32_e32 v87, v86
	s_nop 1
	v_permlane32_swap_b32_e32 v86, v87
	v_max_f32_e32 v86, v86, v87
	v_max_f32_e32 v201, v197, v86
	v_add_f32_e32 v87, 0x41000000, v197
	v_cmp_gt_f32_e32 vcc, v201, v87
	s_cbranch_vccz .LBB0_419
	v_sub_f32_e32 v87, v197, v201
	s_mov_b32 s61, 0
	v_exp_f32_e32 v88, v87
	s_nop 0
	v_mul_f32_e32 v187, v187, v88
	v_pk_mul_f32 v[62:63], v[62:63], v[88:89] op_sel_hi:[1,0]
	v_pk_mul_f32 v[60:61], v[60:61], v[88:89] op_sel_hi:[1,0]
	v_pk_mul_f32 v[58:59], v[58:59], v[88:89] op_sel_hi:[1,0]
	v_pk_mul_f32 v[56:57], v[56:57], v[88:89] op_sel_hi:[1,0]
	v_pk_mul_f32 v[54:55], v[54:55], v[88:89] op_sel_hi:[1,0]
	v_pk_mul_f32 v[52:53], v[52:53], v[88:89] op_sel_hi:[1,0]
	v_pk_mul_f32 v[50:51], v[50:51], v[88:89] op_sel_hi:[1,0]
	v_pk_mul_f32 v[48:49], v[48:49], v[88:89] op_sel_hi:[1,0]
	v_pk_mul_f32 v[46:47], v[46:47], v[88:89] op_sel_hi:[1,0]
	v_pk_mul_f32 v[44:45], v[44:45], v[88:89] op_sel_hi:[1,0]
	v_pk_mul_f32 v[42:43], v[42:43], v[88:89] op_sel_hi:[1,0]
	v_pk_mul_f32 v[40:41], v[40:41], v[88:89] op_sel_hi:[1,0]
	v_pk_mul_f32 v[38:39], v[38:39], v[88:89] op_sel_hi:[1,0]
	v_pk_mul_f32 v[36:37], v[36:37], v[88:89] op_sel_hi:[1,0]
	v_pk_mul_f32 v[34:35], v[34:35], v[88:89] op_sel_hi:[1,0]
	v_pk_mul_f32 v[32:33], v[32:33], v[88:89] op_sel_hi:[1,0]
	v_sub_f32_e32 v86, v86, v201
	v_cmp_gt_f32_e32 vcc, s30, v86
	s_cmp_eq_u64 vcc, exec
	s_cbranch_scc1 .LBB0_420
.LBB0_418:
	s_cmp_lg_u32 s61, 0
	s_cbranch_scc1 .Lr0_A2_fast
	v_sub_f32_e32 v86, v204, v201
	v_sub_f32_e32 v87, v205, v201
	v_sub_f32_e32 v88, v206, v201
	v_sub_f32_e32 v89, v159, v201
	v_sub_f32_e32 v90, v207, v201
	v_sub_f32_e32 v83, v83, v201
	v_sub_f32_e32 v84, v84, v201
	v_sub_f32_e32 v91, v155, v201
	v_exp_f32_e32 v86, v86
	v_exp_f32_e32 v87, v87
	v_exp_f32_e32 v88, v88
	v_exp_f32_e32 v89, v89
	v_exp_f32_e32 v90, v90
	v_exp_f32_e32 v83, v83
	v_exp_f32_e32 v84, v84
	v_exp_f32_e32 v91, v91
	v_sub_f32_e32 v85, v85, v201
	v_sub_f32_e32 v80, v80, v201
	v_sub_f32_e32 v81, v81, v201
	v_sub_f32_e32 v92, v167, v201
	v_sub_f32_e32 v82, v82, v201
	v_sub_f32_e32 v14, v14, v201
	v_sub_f32_e32 v15, v15, v201
	v_sub_f32_e32 v93, v175, v201
	v_exp_f32_e32 v85, v85
	v_exp_f32_e32 v80, v80
	v_exp_f32_e32 v81, v81
	v_exp_f32_e32 v92, v92
	v_exp_f32_e32 v82, v82
	v_exp_f32_e32 v14, v14
	v_exp_f32_e32 v15, v15
	v_exp_f32_e32 v93, v93
.Lr0_A2_join:
	v_cvt_pk_bf16_f32 v100, v86, v87
	v_cvt_pk_bf16_f32 v101, v88, v89
	v_cvt_pk_bf16_f32 v102, v90, v83
	v_cvt_pk_bf16_f32 v103, v84, v91
	v_cvt_pk_bf16_f32 v96, v85, v80
	v_cvt_pk_bf16_f32 v97, v81, v92
	v_cvt_pk_bf16_f32 v98, v82, v14
	v_cvt_pk_bf16_f32 v99, v15, v93
	v_mfma_f32_32x32x16_bf16 v[80:95], v[220:223], v[100:103], 0
	s_nop 0
	v_mfma_f32_32x32x16_bf16 v[80:95], v[220:223], v[96:99], v[80:95]
	s_cbranch_execnz .LBB0_421
	s_branch .LBB0_422

; template <int MODE, int NQ>
; __device__ __forceinline__ void attn_unit(LAS unsigned char* lds, const Params& P, int layer, int b, int h, int qb) {
;     ...
;                 const bool dead = (MODE != 0) && __all(rmrel[cc] < -136.f);
;                 if (dead) { pw[cc][0] = zero8; pw[cc][1] = zero8; }
;                 else {
;                     alive = true;
;                     if (MODE != 0) {
;     ...
;             if (alive)
; #pragma unroll
.LBB0_420:
	v_mov_b32_e32 v80, 0
	v_mov_b32_e32 v96, 0
	v_mov_b32_e32 v97, v96
	v_mov_b32_e32 v98, v96
	v_mov_b32_e32 v99, v96
	v_mov_b32_e32 v100, v96
	v_mov_b32_e32 v101, v96
	v_mov_b32_e32 v102, v96
	v_mov_b32_e32 v103, v96
	s_and_b64 vcc, exec, s[14:15]
	s_cbranch_vccz .LBB0_422

; template <int MODE, int NQ>
; __device__ __forceinline__ void attn_unit(LAS unsigned char* lds, const Params& P, int layer, int b, int h, int qb) {
;     ...
;         const int bnx = (bcur == 2) ? 0 : bcur + 1, bn2 = (bnx == 2) ? 0 : bnx + 1;
;         const LAS unsigned char* cur = lds + bcur * AT_BUF;
;         const LAS unsigned char* nxt = lds + bnx * AT_BUF;
; #pragma unroll
;         for (int hf = 0; hf < 2; ++hf) {
;             if (it + 2 < NT) { if (hf == 0) AT_GLOADK(AT_TILE(it + 2)); else AT_GLOADV(AT_TILE(it + 2)); }
;             f32x16 sc[NC];
; #pragma unroll
;             for (int cc = 0; cc < NC; ++cc) {
;                 sc[cc] = f32x16{};
; #pragma unroll
;                 for (int d0 = 0; d0 < ND0; ++d0) sc[cc] = __builtin_amdgcn_mfma_f32_32x32x16_bf16(kf[(cc % NMAP) * ND0 + d0], qf[cc][d0], sc[cc], 0, 0, 0);
;             }
;             __builtin_amdgcn_sched_barrier(0);
;             AT_VLOAD(cur, hf);
;             if (hf == 0) AT_KLOAD(cur, 1); else if (it + 1 < NT) AT_KLOAD(nxt, 0);
;             __builtin_amdgcn_sched_barrier(0);
;             bf16x8 pw[NC][2]; float rmrel[NC]; bool alive = false;
; #pragma unroll
;             for (int cc = 0; cc < NC; ++cc) {
;                 f32x16& s0 = sc[cc];
;                 float mn;
;                 if (MODE != 0) {
;                     const LAS f32x4* tp4 = (const LAS f32x4*)(tlane + (kt * 64 + hf * 32) * 4);
;                     float rm = -3e38f;
; #pragma unroll
;                     for (int g = 0; g < 4; ++g) { const f32x4 t4 = tp4[2 * g];
; #pragma unroll
;                         for (int i = 0; i < 4; ++i) { s0[4 * g + i] = s0[4 * g + i] * c + t4[i]; rm = fmaxf(rm, s0[4 * g + i]); } }
;                     rm = xmax(rm);
;                     mn = fmaxf(mrun[cc], rm);
;                     rmrel[cc] = rm;
;                 } else {
;                     float rm = -3e38f;
; #pragma unroll
;                     for (int r = 0; r < 16; ++r) rm = fmaxf(rm, s0[r]);
;                     rm = xmax(rm);
;                     mn = fmaxf(mrun[cc], rm * c);
;                 }
;                 if (__any(mn > mrun[cc] + AT_THR)) {
;                     const float al = fast_exp2(mrun[cc] - mn); lrun[cc] *= al;
; #pragma unroll
;                     for (int r = 0; r < 16; ++r) { o[cc][0][r] *= al; o[cc][1][r] *= al; }
;                     mrun[cc] = mn;
;                 }
.LBB0_422:
	s_add_i32 s14, s9, 1
	s_cmp_lg_u32 s9, 2
	s_cselect_b32 s9, s14, 0
	s_mul_i32 s15, s9, 0x5000
	s_add_i32 s10, s15, 0x5000
	s_cmp_lg_u32 s9, 2
	s_cselect_b32 s14, s10, 0
	v_add_u32_e32 v202, s14, v194
	v_add_f32_e32 v187, v187, v80
	v_mfma_f32_32x32x16_bf16 v[96:111], v[132:135], v[124:127], 0
	v_mfma_f32_32x32x16_bf16 v[80:95], v[10:13], v[120:123], 0
	v_mfma_f32_32x32x16_bf16 v[96:111], v[128:131], v[116:119], v[96:111]
	v_mfma_f32_32x32x16_bf16 v[80:95], v[6:9], v[112:115], v[80:95]
	ds_read_b64_tr_b16 v[148:149], v199 offset:14336
	ds_read_b64_tr_b16 v[150:151], v199 offset:14848
	ds_read_b64_tr_b16 v[144:145], v199 offset:15360
	ds_read_b64_tr_b16 v[146:147], v199 offset:15872
	ds_read_b64_tr_b16 v[10:11], v199 offset:18432
	ds_read_b64_tr_b16 v[12:13], v199 offset:18944
	ds_read_b64_tr_b16 v[6:7], v199 offset:19456
	ds_read_b64_tr_b16 v[8:9], v199 offset:19968
	v_add_u32_e32 v14, s15, v190
	ds_read_b128 v[140:143], v14
	ds_read_b128 v[136:139], v14 offset:2048
	ds_read_b128 v[132:135], v14 offset:4096
	ds_read_b128 v[128:131], v14 offset:6144
	ds_read_b128 v[156:159], v0 offset:61568
	ds_read_b128 v[152:155], v0 offset:61600
	ds_read_b128 v[164:167], v0 offset:61632
	ds_read_b128 v[172:175], v0 offset:61664
	s_waitcnt lgkmcnt(3)
	v_pk_fma_f32 v[160:161], v[96:97], s[34:35], v[156:157] op_sel_hi:[1,0,1]
	v_pk_fma_f32 v[98:99], v[98:99], s[34:35], v[158:159] op_sel_hi:[1,0,1]
	v_max3_f32 v96, v160, s68, v161
	s_waitcnt lgkmcnt(2)
	v_pk_fma_f32 v[14:15], v[100:101], s[34:35], v[152:153] op_sel_hi:[1,0,1]
	v_max3_f32 v96, v96, v98, v99
	v_max3_f32 v100, v96, v14, v15
	v_pk_fma_f32 v[96:97], v[102:103], s[34:35], v[154:155] op_sel_hi:[1,0,1]
	s_waitcnt lgkmcnt(1)
	v_pk_fma_f32 v[104:105], v[104:105], s[34:35], v[164:165] op_sel_hi:[1,0,1]
	v_max3_f32 v100, v100, v96, v97
	v_max3_f32 v0, v100, v104, v105
	v_pk_fma_f32 v[100:101], v[106:107], s[34:35], v[166:167] op_sel_hi:[1,0,1]
	s_waitcnt lgkmcnt(0)
	v_pk_fma_f32 v[102:103], v[108:109], s[34:35], v[172:173] op_sel_hi:[1,0,1]
	v_max3_f32 v0, v0, v100, v101
	v_max3_f32 v0, v0, v102, v103
	v_pk_fma_f32 v[106:107], v[110:111], s[34:35], v[174:175] op_sel_hi:[1,0,1]
	s_nop 0
	v_max3_f32 v0, v0, v106, v107
	v_mov_b32_e32 v108, v0
	s_nop 1
	v_permlane32_swap_b32_e32 v0, v108
	v_max_f32_e32 v0, v0, v108
	v_max_f32_e32 v198, v200, v0
	v_add_f32_e32 v108, 0x41000000, v200
	v_cmp_gt_f32_e32 vcc, v198, v108
	s_cbranch_vccz .LBB0_424
	v_sub_f32_e32 v108, v200, v198
	s_mov_b32 s61, 0
	v_exp_f32_e32 v108, v108
	s_nop 0
	v_mul_f32_e32 v188, v188, v108
	v_pk_mul_f32 v[78:79], v[78:79], v[108:109] op_sel_hi:[1,0]
	v_pk_mul_f32 v[76:77], v[76:77], v[108:109] op_sel_hi:[1,0]
	v_pk_mul_f32 v[74:75], v[74:75], v[108:109] op_sel_hi:[1,0]
	v_pk_mul_f32 v[72:73], v[72:73], v[108:109] op_sel_hi:[1,0]
	v_pk_mul_f32 v[70:71], v[70:71], v[108:109] op_sel_hi:[1,0]
	v_pk_mul_f32 v[68:69], v[68:69], v[108:109] op_sel_hi:[1,0]
	v_pk_mul_f32 v[66:67], v[66:67], v[108:109] op_sel_hi:[1,0]
	v_pk_mul_f32 v[64:65], v[64:65], v[108:109] op_sel_hi:[1,0]
	v_pk_mul_f32 v[30:31], v[30:31], v[108:109] op_sel_hi:[1,0]
	v_pk_mul_f32 v[28:29], v[28:29], v[108:109] op_sel_hi:[1,0]
	v_pk_mul_f32 v[26:27], v[26:27], v[108:109] op_sel_hi:[1,0]
	v_pk_mul_f32 v[24:25], v[24:25], v[108:109] op_sel_hi:[1,0]
	v_pk_mul_f32 v[22:23], v[22:23], v[108:109] op_sel_hi:[1,0]
	v_pk_mul_f32 v[20:21], v[20:21], v[108:109] op_sel_hi:[1,0]
	v_pk_mul_f32 v[18:19], v[18:19], v[108:109] op_sel_hi:[1,0]
	v_pk_mul_f32 v[16:17], v[16:17], v[108:109] op_sel_hi:[1,0]
	s_branch .LBB0_425

; template <int MODE, int NQ>
; __device__ __forceinline__ void attn_unit(LAS unsigned char* lds, const Params& P, int layer, int b, int h, int qb) {
;     ...
;                     const LAS f32x4* tp4 = (const LAS f32x4*)(tlane + (kt * 64 + hf * 32) * 4);
;                     float rm = -3e38f;
; #pragma unroll
;                     for (int g = 0; g < 4; ++g) { const f32x4 t4 = tp4[2 * g];
; #pragma unroll
;                         for (int i = 0; i < 4; ++i) { s0[4 * g + i] = s0[4 * g + i] * c + t4[i]; rm = fmaxf(rm, s0[4 * g + i]); } }
;                     rm = xmax(rm);
;                     mn = fmaxf(mrun[cc], rm);
;                     rmrel[cc] = rm;
;                 } else {
;                     float rm = -3e38f;
; #pragma unroll
;                     for (int r = 0; r < 16; ++r) rm = fmaxf(rm, s0[r]);
;                     rm = xmax(rm);
;                     mn = fmaxf(mrun[cc], rm * c);
;                 }
;                 if (__any(mn > mrun[cc] + AT_THR)) {
;                     const float al = fast_exp2(mrun[cc] - mn); lrun[cc] *= al;
; #pragma unroll
;                     for (int r = 0; r < 16; ++r) { o[cc][0][r] *= al; o[cc][1][r] *= al; }
;                     mrun[cc] = mn;
;                 }
;                 mn = mrun[cc];
;                 if (MODE != 0) rmrel[cc] -= mn;
;                 const bool dead = (MODE != 0) && __all(rmrel[cc] < -136.f);
;                 if (dead) { pw[cc][0] = zero8; pw[cc][1] = zero8; }
;                 else {
;                     alive = true;
;                     if (MODE != 0) {
; #pragma unroll
;                         for (int r = 0; r < 16; ++r) s0[r] = fast_exp2(s0[r] - mn);
;                     } else {
;                         const float nm = -mn;
; #pragma unroll
;                         for (int r = 0; r < 16; ++r) s0[r] = fast_exp2(__builtin_fmaf(s0[r], c, nm));
;                     }
;                     u32x4 w;
;                     w.x = cvtpk(s0[0], s0[1]); w.y = cvtpk(s0[2], s0[3]); w.z = cvtpk(s0[4], s0[5]); w.w = cvtpk(s0[6], s0[7]); pw[cc][0] = __builtin_bit_cast(bf16x8, w);
;                     w.x = cvtpk(s0[8], s0[9]); w.y = cvtpk(s0[10], s0[11]); w.z = cvtpk(s0[12], s0[13]); w.w = cvtpk(s0[14], s0[15]); pw[cc][1] = __builtin_bit_cast(bf16x8, w);
;                     f32x16 t = __builtin_amdgcn_mfma_f32_32x32x16_bf16(ones8, pw[cc][0], f32x16{}, 0, 0, 0);
.Lr0_A3_join:
	v_cvt_pk_bf16_f32 v168, v0, v108
	v_cvt_pk_bf16_f32 v169, v98, v99
	v_cvt_pk_bf16_f32 v170, v14, v15
	v_cvt_pk_bf16_f32 v171, v96, v97
	v_cvt_pk_bf16_f32 v160, v104, v105
	v_cvt_pk_bf16_f32 v161, v100, v101
	v_cvt_pk_bf16_f32 v162, v102, v103
	v_cvt_pk_bf16_f32 v163, v106, v107
	v_mfma_f32_32x32x16_bf16 v[96:111], v[220:223], v[168:171], 0
	s_nop 0
	v_mfma_f32_32x32x16_bf16 v[96:111], v[220:223], v[160:163], v[96:111]
	s_branch .LBB0_428
.LBB0_427:
	v_mov_b32_e32 v96, 0
	v_mov_b32_e32 v160, 0
	v_mov_b32_e32 v161, 0
	v_mov_b32_e32 v162, 0
	v_mov_b32_e32 v163, 0
	v_mov_b32_e32 v168, 0
	v_mov_b32_e32 v169, 0
	v_mov_b32_e32 v170, 0
	v_mov_b32_e32 v171, 0
.LBB0_428:
	v_fmamk_f32 v204, v80, 0x3e8293ee, v156
	v_fmamk_f32 v205, v81, 0x3e8293ee, v157
	v_max3_f32 v0, v204, s68, v205
	v_fmamk_f32 v206, v82, 0x3e8293ee, v158
	v_fmac_f32_e32 v159, 0x3e8293ee, v83
	v_max3_f32 v0, v0, v206, v159
	v_fmamk_f32 v207, v84, 0x3e8293ee, v152
	v_fmamk_f32 v82, v85, 0x3e8293ee, v153
	v_max3_f32 v0, v0, v207, v82
	v_fmamk_f32 v83, v86, 0x3e8293ee, v154
	v_fmac_f32_e32 v155, 0x3e8293ee, v87
	v_max3_f32 v0, v0, v83, v155
	v_add_f32_e32 v188, v188, v96
	v_fmamk_f32 v84, v88, 0x3e8293ee, v164
	v_fmamk_f32 v15, v89, 0x3e8293ee, v165
	v_max3_f32 v0, v0, v84, v15
	v_fmamk_f32 v80, v90, 0x3e8293ee, v166
	v_fmac_f32_e32 v167, 0x3e8293ee, v91
	v_max3_f32 v14, v0, v80, v167
	v_fmamk_f32 v81, v92, 0x3e8293ee, v172
	v_fmamk_f32 v0, v93, 0x3e8293ee, v173
	v_max3_f32 v85, v14, v81, v0
	v_fmamk_f32 v14, v94, 0x3e8293ee, v174
	v_fmac_f32_e32 v175, 0x3e8293ee, v95
	v_max3_f32 v85, v85, v14, v175
	v_mov_b32_e32 v86, v85
	s_nop 1
	v_permlane32_swap_b32_e32 v85, v86
	v_max_f32_e32 v85, v85, v86
	v_max_f32_e32 v197, v201, v85
	v_add_f32_e32 v86, 0x41000000, v201
	v_cmp_gt_f32_e32 vcc, v197, v86
	s_cbranch_vccz .LBB0_431
	v_sub_f32_e32 v86, v201, v197
	s_mov_b32 s61, 0
	v_exp_f32_e32 v86, v86
	s_nop 0
	v_mul_f32_e32 v187, v187, v86
	v_pk_mul_f32 v[62:63], v[62:63], v[86:87] op_sel_hi:[1,0]
	v_pk_mul_f32 v[60:61], v[60:61], v[86:87] op_sel_hi:[1,0]
	v_pk_mul_f32 v[58:59], v[58:59], v[86:87] op_sel_hi:[1,0]
	v_pk_mul_f32 v[56:57], v[56:57], v[86:87] op_sel_hi:[1,0]
	v_pk_mul_f32 v[54:55], v[54:55], v[86:87] op_sel_hi:[1,0]
	v_pk_mul_f32 v[52:53], v[52:53], v[86:87] op_sel_hi:[1,0]
	v_pk_mul_f32 v[50:51], v[50:51], v[86:87] op_sel_hi:[1,0]
	v_pk_mul_f32 v[48:49], v[48:49], v[86:87] op_sel_hi:[1,0]
	v_pk_mul_f32 v[46:47], v[46:47], v[86:87] op_sel_hi:[1,0]
	v_pk_mul_f32 v[44:45], v[44:45], v[86:87] op_sel_hi:[1,0]
	v_pk_mul_f32 v[42:43], v[42:43], v[86:87] op_sel_hi:[1,0]
	v_pk_mul_f32 v[40:41], v[40:41], v[86:87] op_sel_hi:[1,0]
	v_pk_mul_f32 v[38:39], v[38:39], v[86:87] op_sel_hi:[1,0]
	v_pk_mul_f32 v[36:37], v[36:37], v[86:87] op_sel_hi:[1,0]
	v_pk_mul_f32 v[34:35], v[34:35], v[86:87] op_sel_hi:[1,0]
	v_pk_mul_f32 v[32:33], v[32:33], v[86:87] op_sel_hi:[1,0]
	v_sub_f32_e32 v85, v85, v197
	v_cmp_gt_f32_e32 vcc, s30, v85
	s_cmp_eq_u64 vcc, exec
	s_cbranch_scc1 .LBB0_432
.LBB0_430:
	s_cmp_lg_u32 s61, 0
	s_cbranch_scc1 .Lr0_A4_fast
	v_sub_f32_e32 v85, v204, v197
	v_sub_f32_e32 v86, v205, v197
	v_sub_f32_e32 v87, v206, v197
	v_sub_f32_e32 v88, v159, v197
	v_sub_f32_e32 v89, v207, v197
	v_sub_f32_e32 v82, v82, v197
	v_sub_f32_e32 v83, v83, v197
	v_sub_f32_e32 v90, v155, v197
	v_exp_f32_e32 v85, v85
	v_exp_f32_e32 v86, v86
	v_exp_f32_e32 v87, v87
	v_exp_f32_e32 v88, v88
	v_exp_f32_e32 v89, v89
	v_exp_f32_e32 v82, v82
	v_exp_f32_e32 v83, v83
	v_exp_f32_e32 v90, v90
	v_sub_f32_e32 v84, v84, v197
	v_sub_f32_e32 v15, v15, v197
	v_sub_f32_e32 v80, v80, v197
	v_sub_f32_e32 v91, v167, v197
	v_sub_f32_e32 v81, v81, v197
	v_sub_f32_e32 v0, v0, v197
	v_sub_f32_e32 v14, v14, v197
	v_sub_f32_e32 v92, v175, v197
	v_exp_f32_e32 v84, v84
	v_exp_f32_e32 v15, v15
	v_exp_f32_e32 v80, v80
	v_exp_f32_e32 v91, v91
	v_exp_f32_e32 v81, v81
	v_exp_f32_e32 v0, v0
	v_exp_f32_e32 v14, v14
	v_exp_f32_e32 v92, v92
.Lr0_A4_join:
	v_cvt_pk_bf16_f32 v100, v85, v86
	v_cvt_pk_bf16_f32 v101, v87, v88
	v_cvt_pk_bf16_f32 v102, v89, v82
	v_cvt_pk_bf16_f32 v103, v83, v90
	v_cvt_pk_bf16_f32 v96, v84, v15
	v_cvt_pk_bf16_f32 v97, v80, v91
	v_cvt_pk_bf16_f32 v98, v81, v0
	v_cvt_pk_bf16_f32 v99, v14, v92
	v_mfma_f32_32x32x16_bf16 v[80:95], v[220:223], v[100:103], 0
	s_nop 0
	v_mfma_f32_32x32x16_bf16 v[80:95], v[220:223], v[96:99], v[80:95]
	s_branch .LBB0_433

; template <int MODE, int NQ>
; __device__ __forceinline__ void attn_unit(LAS unsigned char* lds, const Params& P, int layer, int b, int h, int qb) {
;     ...
;                 const bool dead = (MODE != 0) && __all(rmrel[cc] < -136.f);
;                 if (dead) { pw[cc][0] = zero8; pw[cc][1] = zero8; }
;                 else {
;                     alive = true;
;                     if (MODE != 0) {
;     ...
;             if (alive)
; #pragma unroll
.LBB0_432:
	v_mov_b32_e32 v80, 0
	v_mov_b32_e32 v96, 0
	v_mov_b32_e32 v97, 0
	v_mov_b32_e32 v98, 0
	v_mov_b32_e32 v99, 0
	v_mov_b32_e32 v100, 0
	v_mov_b32_e32 v101, 0
	v_mov_b32_e32 v102, 0
	v_mov_b32_e32 v103, 0
	s_andn2_b64 vcc, exec, s[10:11]
	s_cbranch_vccnz .LBB0_409

; __device__ __forceinline__ float fast_exp2(float x) { return __builtin_amdgcn_exp2f(x); }
; template <int MODE, int NQ>
; __device__ __forceinline__ void attn_unit(LAS unsigned char* lds, const Params& P, int layer, int b, int h, int qb) {
;     ...
;                     if (MODE != 0) {
; #pragma unroll
;                         for (int r = 0; r < 16; ++r) s0[r] = fast_exp2(s0[r] - mn);
;                     } else {
.Lr0_A2_fast:
	v_exp_f32_e32 v86, v204
	v_exp_f32_e32 v87, v205
	v_exp_f32_e32 v88, v206
	v_exp_f32_e32 v89, v159
	v_exp_f32_e32 v90, v207
	v_exp_f32_e32 v83, v83
	v_exp_f32_e32 v84, v84
	v_exp_f32_e32 v91, v155
	v_exp_f32_e32 v85, v85
	v_exp_f32_e32 v80, v80
	v_exp_f32_e32 v81, v81
	v_exp_f32_e32 v92, v167
	v_exp_f32_e32 v82, v82
	v_exp_f32_e32 v14, v14
	v_exp_f32_e32 v15, v15
	v_exp_f32_e32 v93, v175
	s_branch .Lr0_A2_join

; __device__ __forceinline__ float fast_exp2(float x) { return __builtin_amdgcn_exp2f(x); }
; template <int MODE, int NQ>
; __device__ __forceinline__ void attn_unit(LAS unsigned char* lds, const Params& P, int layer, int b, int h, int qb) {
;     ...
;                     if (MODE != 0) {
; #pragma unroll
;                         for (int r = 0; r < 16; ++r) s0[r] = fast_exp2(s0[r] - mn);
;                     } else {
.Lr0_A4_fast:
	v_exp_f32_e32 v85, v204
	v_exp_f32_e32 v86, v205
	v_exp_f32_e32 v87, v206
	v_exp_f32_e32 v88, v159
	v_exp_f32_e32 v89, v207
	v_exp_f32_e32 v82, v82
	v_exp_f32_e32 v83, v83
	v_exp_f32_e32 v90, v155
	v_exp_f32_e32 v84, v84
	v_exp_f32_e32 v15, v15
	v_exp_f32_e32 v80, v80
	v_exp_f32_e32 v91, v167
	v_exp_f32_e32 v81, v81
	v_exp_f32_e32 v0, v0
	v_exp_f32_e32 v14, v14
	v_exp_f32_e32 v92, v175
	s_branch .Lr0_A4_join
